# v41 + PV block V-fragment LDS look-ahead 4 -> 7 fragments (7 rotating buffers)
# baseline (speedup 1.0000x reference)
.LBB0_1608:
	v_add_f32_e32 v14, 0, v170
	v_add_f32_e32 v15, 0, v171
	v_cvt_pk_bf16_f32 v124, v170, v172
	v_add_f32_e32 v14, v172, v14
	v_add_f32_e32 v15, v173, v15
	v_cvt_pk_bf16_f32 v125, v174, v176
	v_add_f32_e32 v14, v174, v14
	v_add_f32_e32 v15, v175, v15
	v_cvt_pk_bf16_f32 v126, v178, v180
	v_add_f32_e32 v14, v176, v14
	v_add_f32_e32 v15, v177, v15
	v_cvt_pk_bf16_f32 v127, v182, v184
	v_add_f32_e32 v14, v178, v14
	v_add_f32_e32 v15, v179, v15
	v_cvt_pk_bf16_f32 v128, v186, v188
	v_add_f32_e32 v14, v180, v14
	v_add_f32_e32 v15, v181, v15
	v_cvt_pk_bf16_f32 v129, v190, v192
	v_add_f32_e32 v14, v182, v14
	v_add_f32_e32 v15, v183, v15
	v_cvt_pk_bf16_f32 v130, v194, v196
	v_add_f32_e32 v14, v184, v14
	v_add_f32_e32 v15, v185, v15
	v_cvt_pk_bf16_f32 v131, v198, v200
	v_add_f32_e32 v14, v186, v14
	v_add_f32_e32 v15, v187, v15
	v_cvt_pk_bf16_f32 v132, v171, v173
	v_add_f32_e32 v14, v188, v14
	v_add_f32_e32 v15, v189, v15
	v_cvt_pk_bf16_f32 v133, v175, v177
	v_add_f32_e32 v14, v190, v14
	v_add_f32_e32 v15, v191, v15
	v_cvt_pk_bf16_f32 v134, v179, v181
	v_add_f32_e32 v14, v192, v14
	v_add_f32_e32 v15, v193, v15
	v_cvt_pk_bf16_f32 v135, v183, v185
	v_add_f32_e32 v14, v194, v14
	v_add_f32_e32 v15, v195, v15
	v_cvt_pk_bf16_f32 v136, v187, v189
	v_add_f32_e32 v14, v196, v14
	v_add_f32_e32 v15, v197, v15
	v_cvt_pk_bf16_f32 v137, v191, v193
	v_add_f32_e32 v14, v198, v14
	v_add_f32_e32 v15, v199, v15
	v_cvt_pk_bf16_f32 v138, v195, v197
	v_add_f32_e32 v14, v200, v14
	v_add_f32_e32 v15, v201, v15
	v_cvt_pk_bf16_f32 v139, v199, v201
	v_add_f32_e32 v0, v14, v15
	s_waitcnt lgkmcnt(7)
	v_mfma_f32_32x32x16_bf16 v[96:111], v[80:83], v[144:147], 0
	v_add_u32_e32 v14, s71, v209
	s_waitcnt lgkmcnt(6)
	v_mfma_f32_32x32x16_bf16 v[80:95], v[84:87], v[144:147], 0
	s_waitcnt lgkmcnt(4)
	v_mfma_f32_32x32x16_bf16 v[80:95], v[112:115], v[148:151], v[80:95]
	v_mfma_f32_32x32x16_bf16 v[96:111], v[6:9], v[148:151], v[96:111]
	s_waitcnt lgkmcnt(2)
	v_mfma_f32_32x32x16_bf16 v[80:95], v[116:119], v[152:155], v[80:95]
	v_mfma_f32_32x32x16_bf16 v[96:111], v[10:13], v[152:155], v[96:111]
	ds_read_b128 v[6:9], v14 offset:16384
	ds_read_b128 v[10:13], v14 offset:16896
	ds_read_b128 v[112:115], v14 offset:17408
	ds_read_b128 v[116:119], v14 offset:17920
	ds_read_b128 v[140:143], v14 offset:20480
	s_waitcnt lgkmcnt(5)
	v_mfma_f32_32x32x16_bf16 v[80:95], v[120:123], v[156:159], v[80:95]
	v_mfma_f32_32x32x16_bf16 v[96:111], v[2:5], v[156:159], v[96:111]
	ds_read_b128 v[2:5], v14 offset:20992
	ds_read_b128 v[120:123], v14 offset:21504
	s_waitcnt lgkmcnt(6)
	v_mfma_f32_32x32x16_bf16 v[64:79], v[6:9], v[124:127], v[64:79]
	ds_read_b128 v[6:9], v14 offset:22016
	s_add_i32 s3, s68, 3
	s_and_b32 s69, s3, 3
	s_lshl_b32 s69, s69, 15
	s_add_i32 s72, s68, 2
	s_and_b32 s72, s72, 3
	s_lshl_b32 s72, s72, 15
	s_add_i32 s71, s68, 1
	s_and_b32 s71, s71, 3
	s_lshl_b32 s71, s71, 15
	s_add_i32 s3, s68, 1
	s_cmp_ge_u32 s3, s65
	s_cselect_b64 s[8:9], -1, 0
	v_exp_f32_e32 v170, v96
	v_exp_f32_e32 v172, v97
	s_waitcnt lgkmcnt(6)
	v_mfma_f32_32x32x16_bf16 v[48:63], v[10:13], v[124:127], v[48:63]
	ds_read_b128 v[10:13], v14 offset:24576
	v_exp_f32_e32 v174, v98
	v_exp_f32_e32 v176, v99
	s_waitcnt lgkmcnt(6)
	v_mfma_f32_32x32x16_bf16 v[32:47], v[112:115], v[124:127], v[32:47]
	ds_read_b128 v[112:115], v14 offset:25088
	v_exp_f32_e32 v178, v100
	v_exp_f32_e32 v180, v101
	s_waitcnt lgkmcnt(6)
	v_mfma_f32_32x32x16_bf16 v[16:31], v[116:119], v[124:127], v[16:31]
	ds_read_b128 v[116:119], v14 offset:25600
	v_exp_f32_e32 v182, v102
	v_exp_f32_e32 v184, v103
	s_waitcnt lgkmcnt(6)
	v_mfma_f32_32x32x16_bf16 v[64:79], v[140:143], v[128:131], v[64:79]
	ds_read_b128 v[140:143], v14 offset:26112
	v_exp_f32_e32 v186, v104
	v_exp_f32_e32 v188, v105
	s_waitcnt lgkmcnt(6)
	v_mfma_f32_32x32x16_bf16 v[48:63], v[2:5], v[128:131], v[48:63]
	ds_read_b128 v[2:5], v14 offset:28672
	v_exp_f32_e32 v190, v106
	v_exp_f32_e32 v192, v107
	s_waitcnt lgkmcnt(6)
	v_mfma_f32_32x32x16_bf16 v[32:47], v[120:123], v[128:131], v[32:47]
	ds_read_b128 v[120:123], v14 offset:29184
	v_exp_f32_e32 v194, v108
	v_exp_f32_e32 v196, v109
	s_waitcnt lgkmcnt(6)
	v_mfma_f32_32x32x16_bf16 v[16:31], v[6:9], v[128:131], v[16:31]
	ds_read_b128 v[6:9], v14 offset:29696
	v_exp_f32_e32 v198, v110
	v_exp_f32_e32 v200, v111
	s_waitcnt lgkmcnt(6)
	v_mfma_f32_32x32x16_bf16 v[64:79], v[10:13], v[132:135], v[64:79]
	ds_read_b128 v[10:13], v14 offset:30208
	v_exp_f32_e32 v171, v80
	v_exp_f32_e32 v173, v81
	s_waitcnt lgkmcnt(6)
	v_mfma_f32_32x32x16_bf16 v[48:63], v[112:115], v[132:135], v[48:63]
	v_exp_f32_e32 v175, v82
	v_exp_f32_e32 v177, v83
	s_waitcnt lgkmcnt(5)
	v_mfma_f32_32x32x16_bf16 v[32:47], v[116:119], v[132:135], v[32:47]
	v_exp_f32_e32 v179, v84
	v_exp_f32_e32 v181, v85
	s_waitcnt lgkmcnt(4)
	v_mfma_f32_32x32x16_bf16 v[16:31], v[140:143], v[132:135], v[16:31]
	v_exp_f32_e32 v183, v86
	v_exp_f32_e32 v185, v87
	s_waitcnt lgkmcnt(3)
	v_mfma_f32_32x32x16_bf16 v[64:79], v[2:5], v[136:139], v[64:79]
	v_exp_f32_e32 v187, v88
	v_exp_f32_e32 v189, v89
	s_waitcnt lgkmcnt(2)
	v_mfma_f32_32x32x16_bf16 v[48:63], v[120:123], v[136:139], v[48:63]
	v_exp_f32_e32 v191, v90
	v_exp_f32_e32 v193, v91
	s_waitcnt lgkmcnt(1)
	v_mfma_f32_32x32x16_bf16 v[32:47], v[6:9], v[136:139], v[32:47]
	v_exp_f32_e32 v195, v92
	v_exp_f32_e32 v197, v93
	s_waitcnt lgkmcnt(0)
	v_mfma_f32_32x32x16_bf16 v[16:31], v[10:13], v[136:139], v[16:31]
	v_exp_f32_e32 v199, v94
	v_exp_f32_e32 v201, v95
	v_add_f32_e32 v210, v210, v0

.Lyka_ytop:
	s_cmp_ge_u32 s68, s59
	s_cbranch_scc1 .Lyka_ytail
	v_add_u32_e32 v0, s72, v208
	ds_read_b128 v[80:83], v0
	ds_read_b128 v[84:87], v0 offset:512
	ds_read_b128 v[6:9], v0 offset:2048
	ds_read_b128 v[112:115], v0 offset:2560
	ds_read_b128 v[10:13], v0 offset:4096
	ds_read_b128 v[116:119], v0 offset:4608
	ds_read_b128 v[2:5], v0 offset:6144
	ds_read_b128 v[120:123], v0 offset:6656
	v_add_f32_e32 v14, 0, v170
	v_add_f32_e32 v15, 0, v171
	v_cvt_pk_bf16_f32 v124, v170, v172
	v_add_f32_e32 v14, v172, v14
	v_add_f32_e32 v15, v173, v15
	v_cvt_pk_bf16_f32 v125, v174, v176
	v_add_f32_e32 v14, v174, v14
	v_add_f32_e32 v15, v175, v15
	v_cvt_pk_bf16_f32 v126, v178, v180
	v_add_f32_e32 v14, v176, v14
	v_add_f32_e32 v15, v177, v15
	v_cvt_pk_bf16_f32 v127, v182, v184
	v_add_f32_e32 v14, v178, v14
	v_add_f32_e32 v15, v179, v15
	v_cvt_pk_bf16_f32 v128, v186, v188
	v_add_f32_e32 v14, v180, v14
	v_add_f32_e32 v15, v181, v15
	v_cvt_pk_bf16_f32 v129, v190, v192
	v_add_f32_e32 v14, v182, v14
	v_add_f32_e32 v15, v183, v15
	v_cvt_pk_bf16_f32 v130, v194, v196
	v_add_f32_e32 v14, v184, v14
	v_add_f32_e32 v15, v185, v15
	v_cvt_pk_bf16_f32 v131, v198, v200
	v_add_f32_e32 v14, v186, v14
	v_add_f32_e32 v15, v187, v15
	v_cvt_pk_bf16_f32 v132, v171, v173
	v_add_f32_e32 v14, v188, v14
	v_add_f32_e32 v15, v189, v15
	v_cvt_pk_bf16_f32 v133, v175, v177
	v_add_f32_e32 v14, v190, v14
	v_add_f32_e32 v15, v191, v15
	v_cvt_pk_bf16_f32 v134, v179, v181
	v_add_f32_e32 v14, v192, v14
	v_add_f32_e32 v15, v193, v15
	v_cvt_pk_bf16_f32 v135, v183, v185
	v_add_f32_e32 v14, v194, v14
	v_add_f32_e32 v15, v195, v15
	v_cvt_pk_bf16_f32 v136, v187, v189
	v_add_f32_e32 v14, v196, v14
	v_add_f32_e32 v15, v197, v15
	v_cvt_pk_bf16_f32 v137, v191, v193
	v_add_f32_e32 v14, v198, v14
	v_add_f32_e32 v15, v199, v15
	v_cvt_pk_bf16_f32 v138, v195, v197
	v_add_f32_e32 v14, v200, v14
	v_add_f32_e32 v15, v201, v15
	v_cvt_pk_bf16_f32 v139, v199, v201
	v_add_f32_e32 v0, v14, v15
	s_waitcnt lgkmcnt(7)
	v_mfma_f32_32x32x16_bf16 v[96:111], v[80:83], v[144:147], 0
	v_add_u32_e32 v14, s71, v209
	s_waitcnt lgkmcnt(6)
	v_mfma_f32_32x32x16_bf16 v[80:95], v[84:87], v[144:147], 0
	s_waitcnt lgkmcnt(4)
	v_mfma_f32_32x32x16_bf16 v[80:95], v[112:115], v[148:151], v[80:95]
	v_mfma_f32_32x32x16_bf16 v[96:111], v[6:9], v[148:151], v[96:111]
	s_waitcnt lgkmcnt(2)
	v_mfma_f32_32x32x16_bf16 v[80:95], v[116:119], v[152:155], v[80:95]
	v_mfma_f32_32x32x16_bf16 v[96:111], v[10:13], v[152:155], v[96:111]
	ds_read_b128 v[6:9], v14 offset:16384
	ds_read_b128 v[10:13], v14 offset:16896
	ds_read_b128 v[112:115], v14 offset:17408
	ds_read_b128 v[116:119], v14 offset:17920
	ds_read_b128 v[140:143], v14 offset:20480
	s_waitcnt lgkmcnt(5)
	v_mfma_f32_32x32x16_bf16 v[80:95], v[120:123], v[156:159], v[80:95]
	v_mfma_f32_32x32x16_bf16 v[96:111], v[2:5], v[156:159], v[96:111]
	s_waitcnt vmcnt(0)
	s_barrier
	s_add_i32 s3, s68, 3
	s_cmp_lt_u32 s3, s67
	s_cbranch_scc0 .Lyka_ynodma
	s_add_i32 s3, s69, s66
	s_mov_b32 m0, s3
	v_lshl_add_u64 v[120:121], v[168:169], 0, s[28:29]
	global_load_lds_dwordx4 v[168:169], off
	s_add_i32 m0, s3, 0x2000
	s_nop 0
	global_load_lds_dwordx4 v[120:121], off
	v_lshl_add_u64 v[120:121], v[168:169], 0, s[40:41]
	s_add_i32 m0, s3, 0x4000
	s_nop 0
	global_load_lds_dwordx4 v[120:121], off
	v_lshl_add_u64 v[120:121], v[168:169], 0, s[80:81]
	s_add_i32 m0, s3, 0x6000
	s_nop 0
	global_load_lds_dwordx4 v[120:121], off
.Lyka_ynodma:
	ds_read_b128 v[2:5], v14 offset:20992
	ds_read_b128 v[120:123], v14 offset:21504
	s_waitcnt lgkmcnt(6)
	v_mfma_f32_32x32x16_bf16 v[64:79], v[6:9], v[124:127], v[64:79]
	ds_read_b128 v[6:9], v14 offset:22016
	s_add_i32 s3, s68, 4
	s_and_b32 s69, s3, 3
	s_lshl_b32 s69, s69, 15
	s_add_i32 s72, s68, 2
	s_and_b32 s72, s72, 3
	s_lshl_b32 s72, s72, 15
	s_add_i32 s71, s68, 1
	s_and_b32 s71, s71, 3
	s_lshl_b32 s71, s71, 15
	v_exp_f32_e32 v170, v96
	v_exp_f32_e32 v172, v97
	s_waitcnt lgkmcnt(6)
	v_mfma_f32_32x32x16_bf16 v[48:63], v[10:13], v[124:127], v[48:63]
	ds_read_b128 v[10:13], v14 offset:24576
	v_exp_f32_e32 v174, v98
	v_exp_f32_e32 v176, v99
	s_waitcnt lgkmcnt(6)
	v_mfma_f32_32x32x16_bf16 v[32:47], v[112:115], v[124:127], v[32:47]
	ds_read_b128 v[112:115], v14 offset:25088
	v_exp_f32_e32 v178, v100
	v_exp_f32_e32 v180, v101
	s_waitcnt lgkmcnt(6)
	v_mfma_f32_32x32x16_bf16 v[16:31], v[116:119], v[124:127], v[16:31]
	ds_read_b128 v[116:119], v14 offset:25600
	v_exp_f32_e32 v182, v102
	v_exp_f32_e32 v184, v103
	s_waitcnt lgkmcnt(6)
	v_mfma_f32_32x32x16_bf16 v[64:79], v[140:143], v[128:131], v[64:79]
	ds_read_b128 v[140:143], v14 offset:26112
	v_exp_f32_e32 v186, v104
	v_exp_f32_e32 v188, v105
	s_waitcnt lgkmcnt(6)
	v_mfma_f32_32x32x16_bf16 v[48:63], v[2:5], v[128:131], v[48:63]
	ds_read_b128 v[2:5], v14 offset:28672
	v_exp_f32_e32 v190, v106
	v_exp_f32_e32 v192, v107
	s_waitcnt lgkmcnt(6)
	v_mfma_f32_32x32x16_bf16 v[32:47], v[120:123], v[128:131], v[32:47]
	ds_read_b128 v[120:123], v14 offset:29184
	v_exp_f32_e32 v194, v108
	v_exp_f32_e32 v196, v109
	s_waitcnt lgkmcnt(6)
	v_mfma_f32_32x32x16_bf16 v[16:31], v[6:9], v[128:131], v[16:31]
	ds_read_b128 v[6:9], v14 offset:29696
	v_exp_f32_e32 v198, v110
	v_exp_f32_e32 v200, v111
	s_waitcnt lgkmcnt(6)
	v_mfma_f32_32x32x16_bf16 v[64:79], v[10:13], v[132:135], v[64:79]
	ds_read_b128 v[10:13], v14 offset:30208
	v_exp_f32_e32 v171, v80
	v_exp_f32_e32 v173, v81
	s_waitcnt lgkmcnt(6)
	v_mfma_f32_32x32x16_bf16 v[48:63], v[112:115], v[132:135], v[48:63]
	v_exp_f32_e32 v175, v82
	v_exp_f32_e32 v177, v83
	s_waitcnt lgkmcnt(5)
	v_mfma_f32_32x32x16_bf16 v[32:47], v[116:119], v[132:135], v[32:47]
	v_exp_f32_e32 v179, v84
	v_exp_f32_e32 v181, v85
	s_waitcnt lgkmcnt(4)
	v_mfma_f32_32x32x16_bf16 v[16:31], v[140:143], v[132:135], v[16:31]
	v_exp_f32_e32 v183, v86
	v_exp_f32_e32 v185, v87
	s_waitcnt lgkmcnt(3)
	v_mfma_f32_32x32x16_bf16 v[64:79], v[2:5], v[136:139], v[64:79]
	v_exp_f32_e32 v187, v88
	v_exp_f32_e32 v189, v89
	s_waitcnt lgkmcnt(2)
	v_mfma_f32_32x32x16_bf16 v[48:63], v[120:123], v[136:139], v[48:63]
	v_exp_f32_e32 v191, v90
	v_exp_f32_e32 v193, v91
	s_waitcnt lgkmcnt(1)
	v_mfma_f32_32x32x16_bf16 v[32:47], v[6:9], v[136:139], v[32:47]
	v_exp_f32_e32 v195, v92
	v_exp_f32_e32 v197, v93
	s_waitcnt lgkmcnt(0)
	v_mfma_f32_32x32x16_bf16 v[16:31], v[10:13], v[136:139], v[16:31]
	v_exp_f32_e32 v199, v94
	v_exp_f32_e32 v201, v95
	v_add_f32_e32 v210, v210, v0

.LBB0_2161:
	v_add_f32_e32 v14, 0, v168
	v_add_f32_e32 v15, 0, v169
	v_cvt_pk_bf16_f32 v124, v168, v172
	v_add_f32_e32 v14, v172, v14
	v_add_f32_e32 v15, v173, v15
	v_cvt_pk_bf16_f32 v125, v174, v176
	v_add_f32_e32 v14, v174, v14
	v_add_f32_e32 v15, v175, v15
	v_cvt_pk_bf16_f32 v126, v178, v180
	v_add_f32_e32 v14, v176, v14
	v_add_f32_e32 v15, v177, v15
	v_cvt_pk_bf16_f32 v127, v182, v184
	v_add_f32_e32 v14, v178, v14
	v_add_f32_e32 v15, v179, v15
	v_cvt_pk_bf16_f32 v128, v186, v188
	v_add_f32_e32 v14, v180, v14
	v_add_f32_e32 v15, v181, v15
	v_cvt_pk_bf16_f32 v129, v190, v192
	v_add_f32_e32 v14, v182, v14
	v_add_f32_e32 v15, v183, v15
	v_cvt_pk_bf16_f32 v130, v194, v196
	v_add_f32_e32 v14, v184, v14
	v_add_f32_e32 v15, v185, v15
	v_cvt_pk_bf16_f32 v131, v198, v200
	v_add_f32_e32 v14, v186, v14
	v_add_f32_e32 v15, v187, v15
	v_cvt_pk_bf16_f32 v132, v169, v173
	v_add_f32_e32 v14, v188, v14
	v_add_f32_e32 v15, v189, v15
	v_cvt_pk_bf16_f32 v133, v175, v177
	v_add_f32_e32 v14, v190, v14
	v_add_f32_e32 v15, v191, v15
	v_cvt_pk_bf16_f32 v134, v179, v181
	v_add_f32_e32 v14, v192, v14
	v_add_f32_e32 v15, v193, v15
	v_cvt_pk_bf16_f32 v135, v183, v185
	v_add_f32_e32 v14, v194, v14
	v_add_f32_e32 v15, v195, v15
	v_cvt_pk_bf16_f32 v136, v187, v189
	v_add_f32_e32 v14, v196, v14
	v_add_f32_e32 v15, v197, v15
	v_cvt_pk_bf16_f32 v137, v191, v193
	v_add_f32_e32 v14, v198, v14
	v_add_f32_e32 v15, v199, v15
	v_cvt_pk_bf16_f32 v138, v195, v197
	v_add_f32_e32 v14, v200, v14
	v_add_f32_e32 v15, v201, v15
	v_cvt_pk_bf16_f32 v139, v199, v201
	v_add_f32_e32 v0, v14, v15
	s_waitcnt lgkmcnt(7)
	v_mfma_f32_32x32x16_bf16 v[96:111], v[80:83], v[144:147], 0
	v_add_u32_e32 v14, s80, v209
	s_waitcnt lgkmcnt(6)
	v_mfma_f32_32x32x16_bf16 v[80:95], v[84:87], v[144:147], 0
	s_waitcnt lgkmcnt(4)
	v_mfma_f32_32x32x16_bf16 v[80:95], v[112:115], v[148:151], v[80:95]
	v_mfma_f32_32x32x16_bf16 v[96:111], v[6:9], v[148:151], v[96:111]
	s_waitcnt lgkmcnt(2)
	v_mfma_f32_32x32x16_bf16 v[80:95], v[116:119], v[152:155], v[80:95]
	v_mfma_f32_32x32x16_bf16 v[96:111], v[10:13], v[152:155], v[96:111]
	ds_read_b128 v[6:9], v14 offset:16384
	ds_read_b128 v[10:13], v14 offset:16896
	ds_read_b128 v[112:115], v14 offset:17408
	ds_read_b128 v[116:119], v14 offset:17920
	ds_read_b128 v[140:143], v14 offset:20480
	s_waitcnt lgkmcnt(5)
	v_mfma_f32_32x32x16_bf16 v[80:95], v[120:123], v[156:159], v[80:95]
	v_mfma_f32_32x32x16_bf16 v[96:111], v[2:5], v[156:159], v[96:111]
	ds_read_b128 v[2:5], v14 offset:20992
	ds_read_b128 v[120:123], v14 offset:21504
	s_waitcnt lgkmcnt(6)
	v_mfma_f32_32x32x16_bf16 v[64:79], v[6:9], v[124:127], v[64:79]
	ds_read_b128 v[6:9], v14 offset:22016
	s_add_i32 s3, s78, 3
	s_and_b32 s79, s3, 3
	s_lshl_b32 s79, s79, 15
	s_add_i32 s81, s78, 2
	s_and_b32 s81, s81, 3
	s_lshl_b32 s81, s81, 15
	s_add_i32 s80, s78, 1
	s_and_b32 s80, s80, 3
	s_lshl_b32 s80, s80, 15
	s_add_i32 s3, s78, 1
	s_cmp_ge_u32 s3, s67
	s_cselect_b64 s[8:9], -1, 0
	v_exp_f32_e32 v168, v96
	v_exp_f32_e32 v172, v97
	s_waitcnt lgkmcnt(6)
	v_mfma_f32_32x32x16_bf16 v[48:63], v[10:13], v[124:127], v[48:63]
	ds_read_b128 v[10:13], v14 offset:24576
	v_exp_f32_e32 v174, v98
	v_exp_f32_e32 v176, v99
	s_waitcnt lgkmcnt(6)
	v_mfma_f32_32x32x16_bf16 v[32:47], v[112:115], v[124:127], v[32:47]
	ds_read_b128 v[112:115], v14 offset:25088
	v_exp_f32_e32 v178, v100
	v_exp_f32_e32 v180, v101
	s_waitcnt lgkmcnt(6)
	v_mfma_f32_32x32x16_bf16 v[16:31], v[116:119], v[124:127], v[16:31]
	ds_read_b128 v[116:119], v14 offset:25600
	v_exp_f32_e32 v182, v102
	v_exp_f32_e32 v184, v103
	s_waitcnt lgkmcnt(6)
	v_mfma_f32_32x32x16_bf16 v[64:79], v[140:143], v[128:131], v[64:79]
	ds_read_b128 v[140:143], v14 offset:26112
	v_exp_f32_e32 v186, v104
	v_exp_f32_e32 v188, v105
	s_waitcnt lgkmcnt(6)
	v_mfma_f32_32x32x16_bf16 v[48:63], v[2:5], v[128:131], v[48:63]
	ds_read_b128 v[2:5], v14 offset:28672
	v_exp_f32_e32 v190, v106
	v_exp_f32_e32 v192, v107
	s_waitcnt lgkmcnt(6)
	v_mfma_f32_32x32x16_bf16 v[32:47], v[120:123], v[128:131], v[32:47]
	ds_read_b128 v[120:123], v14 offset:29184
	v_exp_f32_e32 v194, v108
	v_exp_f32_e32 v196, v109
	s_waitcnt lgkmcnt(6)
	v_mfma_f32_32x32x16_bf16 v[16:31], v[6:9], v[128:131], v[16:31]
	ds_read_b128 v[6:9], v14 offset:29696
	v_exp_f32_e32 v198, v110
	v_exp_f32_e32 v200, v111
	s_waitcnt lgkmcnt(6)
	v_mfma_f32_32x32x16_bf16 v[64:79], v[10:13], v[132:135], v[64:79]
	ds_read_b128 v[10:13], v14 offset:30208
	v_exp_f32_e32 v169, v80
	v_exp_f32_e32 v173, v81
	s_waitcnt lgkmcnt(6)
	v_mfma_f32_32x32x16_bf16 v[48:63], v[112:115], v[132:135], v[48:63]
	v_exp_f32_e32 v175, v82
	v_exp_f32_e32 v177, v83
	s_waitcnt lgkmcnt(5)
	v_mfma_f32_32x32x16_bf16 v[32:47], v[116:119], v[132:135], v[32:47]
	v_exp_f32_e32 v179, v84
	v_exp_f32_e32 v181, v85
	s_waitcnt lgkmcnt(4)
	v_mfma_f32_32x32x16_bf16 v[16:31], v[140:143], v[132:135], v[16:31]
	v_exp_f32_e32 v183, v86
	v_exp_f32_e32 v185, v87
	s_waitcnt lgkmcnt(3)
	v_mfma_f32_32x32x16_bf16 v[64:79], v[2:5], v[136:139], v[64:79]
	v_exp_f32_e32 v187, v88
	v_exp_f32_e32 v189, v89
	s_waitcnt lgkmcnt(2)
	v_mfma_f32_32x32x16_bf16 v[48:63], v[120:123], v[136:139], v[48:63]
	v_exp_f32_e32 v191, v90
	v_exp_f32_e32 v193, v91
	s_waitcnt lgkmcnt(1)
	v_mfma_f32_32x32x16_bf16 v[32:47], v[6:9], v[136:139], v[32:47]
	v_exp_f32_e32 v195, v92
	v_exp_f32_e32 v197, v93
	s_waitcnt lgkmcnt(0)
	v_mfma_f32_32x32x16_bf16 v[16:31], v[10:13], v[136:139], v[16:31]
	v_exp_f32_e32 v199, v94
	v_exp_f32_e32 v201, v95
	v_add_f32_e32 v210, v210, v0

.Lykb_ytop:
	s_cmp_ge_u32 s78, s66
	s_cbranch_scc1 .Lykb_ytail
	v_add_u32_e32 v0, s81, v208
	ds_read_b128 v[80:83], v0
	ds_read_b128 v[84:87], v0 offset:512
	ds_read_b128 v[6:9], v0 offset:2048
	ds_read_b128 v[112:115], v0 offset:2560
	ds_read_b128 v[10:13], v0 offset:4096
	ds_read_b128 v[116:119], v0 offset:4608
	ds_read_b128 v[2:5], v0 offset:6144
	ds_read_b128 v[120:123], v0 offset:6656
	v_add_f32_e32 v14, 0, v168
	v_add_f32_e32 v15, 0, v169
	v_cvt_pk_bf16_f32 v124, v168, v172
	v_add_f32_e32 v14, v172, v14
	v_add_f32_e32 v15, v173, v15
	v_cvt_pk_bf16_f32 v125, v174, v176
	v_add_f32_e32 v14, v174, v14
	v_add_f32_e32 v15, v175, v15
	v_cvt_pk_bf16_f32 v126, v178, v180
	v_add_f32_e32 v14, v176, v14
	v_add_f32_e32 v15, v177, v15
	v_cvt_pk_bf16_f32 v127, v182, v184
	v_add_f32_e32 v14, v178, v14
	v_add_f32_e32 v15, v179, v15
	v_cvt_pk_bf16_f32 v128, v186, v188
	v_add_f32_e32 v14, v180, v14
	v_add_f32_e32 v15, v181, v15
	v_cvt_pk_bf16_f32 v129, v190, v192
	v_add_f32_e32 v14, v182, v14
	v_add_f32_e32 v15, v183, v15
	v_cvt_pk_bf16_f32 v130, v194, v196
	v_add_f32_e32 v14, v184, v14
	v_add_f32_e32 v15, v185, v15
	v_cvt_pk_bf16_f32 v131, v198, v200
	v_add_f32_e32 v14, v186, v14
	v_add_f32_e32 v15, v187, v15
	v_cvt_pk_bf16_f32 v132, v169, v173
	v_add_f32_e32 v14, v188, v14
	v_add_f32_e32 v15, v189, v15
	v_cvt_pk_bf16_f32 v133, v175, v177
	v_add_f32_e32 v14, v190, v14
	v_add_f32_e32 v15, v191, v15
	v_cvt_pk_bf16_f32 v134, v179, v181
	v_add_f32_e32 v14, v192, v14
	v_add_f32_e32 v15, v193, v15
	v_cvt_pk_bf16_f32 v135, v183, v185
	v_add_f32_e32 v14, v194, v14
	v_add_f32_e32 v15, v195, v15
	v_cvt_pk_bf16_f32 v136, v187, v189
	v_add_f32_e32 v14, v196, v14
	v_add_f32_e32 v15, v197, v15
	v_cvt_pk_bf16_f32 v137, v191, v193
	v_add_f32_e32 v14, v198, v14
	v_add_f32_e32 v15, v199, v15
	v_cvt_pk_bf16_f32 v138, v195, v197
	v_add_f32_e32 v14, v200, v14
	v_add_f32_e32 v15, v201, v15
	v_cvt_pk_bf16_f32 v139, v199, v201
	v_add_f32_e32 v0, v14, v15
	s_waitcnt lgkmcnt(7)
	v_mfma_f32_32x32x16_bf16 v[96:111], v[80:83], v[144:147], 0
	v_add_u32_e32 v14, s80, v209
	s_waitcnt lgkmcnt(6)
	v_mfma_f32_32x32x16_bf16 v[80:95], v[84:87], v[144:147], 0
	s_waitcnt lgkmcnt(4)
	v_mfma_f32_32x32x16_bf16 v[80:95], v[112:115], v[148:151], v[80:95]
	v_mfma_f32_32x32x16_bf16 v[96:111], v[6:9], v[148:151], v[96:111]
	s_waitcnt lgkmcnt(2)
	v_mfma_f32_32x32x16_bf16 v[80:95], v[116:119], v[152:155], v[80:95]
	v_mfma_f32_32x32x16_bf16 v[96:111], v[10:13], v[152:155], v[96:111]
	ds_read_b128 v[6:9], v14 offset:16384
	ds_read_b128 v[10:13], v14 offset:16896
	ds_read_b128 v[112:115], v14 offset:17408
	ds_read_b128 v[116:119], v14 offset:17920
	ds_read_b128 v[140:143], v14 offset:20480
	s_waitcnt lgkmcnt(5)
	v_mfma_f32_32x32x16_bf16 v[80:95], v[120:123], v[156:159], v[80:95]
	v_mfma_f32_32x32x16_bf16 v[96:111], v[2:5], v[156:159], v[96:111]
	s_waitcnt vmcnt(0)
	s_barrier
	s_add_i32 s3, s78, 3
	s_cmp_lt_u32 s3, s69
	s_cbranch_scc0 .Lykb_ynodma
	s_add_i32 s3, s79, s68
	s_mov_b32 m0, s3
	v_lshl_add_u64 v[120:121], v[170:171], 0, s[24:25]
	global_load_lds_dwordx4 v[170:171], off
	s_add_i32 m0, s3, 0x2000
	s_nop 0
	global_load_lds_dwordx4 v[120:121], off
	v_lshl_add_u64 v[120:121], v[170:171], 0, s[26:27]
	s_add_i32 m0, s3, 0x4000
	s_nop 0
	global_load_lds_dwordx4 v[120:121], off
	v_lshl_add_u64 v[120:121], v[170:171], 0, s[44:45]
	s_add_i32 m0, s3, 0x6000
	s_nop 0
	global_load_lds_dwordx4 v[120:121], off
.Lykb_ynodma:
	ds_read_b128 v[2:5], v14 offset:20992
	ds_read_b128 v[120:123], v14 offset:21504
	s_waitcnt lgkmcnt(6)
	v_mfma_f32_32x32x16_bf16 v[64:79], v[6:9], v[124:127], v[64:79]
	ds_read_b128 v[6:9], v14 offset:22016
	s_add_i32 s3, s78, 4
	s_and_b32 s79, s3, 3
	s_lshl_b32 s79, s79, 15
	s_add_i32 s81, s78, 2
	s_and_b32 s81, s81, 3
	s_lshl_b32 s81, s81, 15
	s_add_i32 s80, s78, 1
	s_and_b32 s80, s80, 3
	s_lshl_b32 s80, s80, 15
	v_exp_f32_e32 v168, v96
	v_exp_f32_e32 v172, v97
	s_waitcnt lgkmcnt(6)
	v_mfma_f32_32x32x16_bf16 v[48:63], v[10:13], v[124:127], v[48:63]
	ds_read_b128 v[10:13], v14 offset:24576
	v_exp_f32_e32 v174, v98
	v_exp_f32_e32 v176, v99
	s_waitcnt lgkmcnt(6)
	v_mfma_f32_32x32x16_bf16 v[32:47], v[112:115], v[124:127], v[32:47]
	ds_read_b128 v[112:115], v14 offset:25088
	v_exp_f32_e32 v178, v100
	v_exp_f32_e32 v180, v101
	s_waitcnt lgkmcnt(6)
	v_mfma_f32_32x32x16_bf16 v[16:31], v[116:119], v[124:127], v[16:31]
	ds_read_b128 v[116:119], v14 offset:25600
	v_exp_f32_e32 v182, v102
	v_exp_f32_e32 v184, v103
	s_waitcnt lgkmcnt(6)
	v_mfma_f32_32x32x16_bf16 v[64:79], v[140:143], v[128:131], v[64:79]
	ds_read_b128 v[140:143], v14 offset:26112
	v_exp_f32_e32 v186, v104
	v_exp_f32_e32 v188, v105
	s_waitcnt lgkmcnt(6)
	v_mfma_f32_32x32x16_bf16 v[48:63], v[2:5], v[128:131], v[48:63]
	ds_read_b128 v[2:5], v14 offset:28672
	v_exp_f32_e32 v190, v106
	v_exp_f32_e32 v192, v107
	s_waitcnt lgkmcnt(6)
	v_mfma_f32_32x32x16_bf16 v[32:47], v[120:123], v[128:131], v[32:47]
	ds_read_b128 v[120:123], v14 offset:29184
	v_exp_f32_e32 v194, v108
	v_exp_f32_e32 v196, v109
	s_waitcnt lgkmcnt(6)
	v_mfma_f32_32x32x16_bf16 v[16:31], v[6:9], v[128:131], v[16:31]
	ds_read_b128 v[6:9], v14 offset:29696
	v_exp_f32_e32 v198, v110
	v_exp_f32_e32 v200, v111
	s_waitcnt lgkmcnt(6)
	v_mfma_f32_32x32x16_bf16 v[64:79], v[10:13], v[132:135], v[64:79]
	ds_read_b128 v[10:13], v14 offset:30208
	v_exp_f32_e32 v169, v80
	v_exp_f32_e32 v173, v81
	s_waitcnt lgkmcnt(6)
	v_mfma_f32_32x32x16_bf16 v[48:63], v[112:115], v[132:135], v[48:63]
	v_exp_f32_e32 v175, v82
	v_exp_f32_e32 v177, v83
	s_waitcnt lgkmcnt(5)
	v_mfma_f32_32x32x16_bf16 v[32:47], v[116:119], v[132:135], v[32:47]
	v_exp_f32_e32 v179, v84
	v_exp_f32_e32 v181, v85
	s_waitcnt lgkmcnt(4)
	v_mfma_f32_32x32x16_bf16 v[16:31], v[140:143], v[132:135], v[16:31]
	v_exp_f32_e32 v183, v86
	v_exp_f32_e32 v185, v87
	s_waitcnt lgkmcnt(3)
	v_mfma_f32_32x32x16_bf16 v[64:79], v[2:5], v[136:139], v[64:79]
	v_exp_f32_e32 v187, v88
	v_exp_f32_e32 v189, v89
	s_waitcnt lgkmcnt(2)
	v_mfma_f32_32x32x16_bf16 v[48:63], v[120:123], v[136:139], v[48:63]
	v_exp_f32_e32 v191, v90
	v_exp_f32_e32 v193, v91
	s_waitcnt lgkmcnt(1)
	v_mfma_f32_32x32x16_bf16 v[32:47], v[6:9], v[136:139], v[32:47]
	v_exp_f32_e32 v195, v92
	v_exp_f32_e32 v197, v93
	s_waitcnt lgkmcnt(0)
	v_mfma_f32_32x32x16_bf16 v[16:31], v[10:13], v[136:139], v[16:31]
	v_exp_f32_e32 v199, v94
	v_exp_f32_e32 v201, v95
	v_add_f32_e32 v210, v210, v0
